# speedup vs baseline: 1.0076x; 1.0013x over previous
; #define PG8_STAGE(bufoff, gbase, voff) do { _Pragma("unroll") for (int _i = 0; _i < 2; ++_i) \
;         __builtin_amdgcn_global_load_lds((const unsigned*)((const char*)(gbase) + (voff)[_i]), (LAS unsigned*)(lds + (bufoff) + ldsw + _i * 8192), 16, 0, 0); } while (0)
; #define PG8_WAIT_V(n) asm volatile("s_waitcnt vmcnt(" #n ")" ::: "memory")
; #define PG8_BAR __builtin_amdgcn_s_barrier()
; template <class Epi, class Sched, bool FUSED = false, bool APERM = false>
; __device__ __forceinline__ void gemm_phase(int wid_s, LAS unsigned char* lds, const Gemm g, const Sched& S, const Epi& E) {
;     ...
;     const char* cA = (const char*)g.A + (size_t)cur.pm * tstep; const char* cB = (const char*)g.Bt + (size_t)cur.pn * tstep;
;     S.a_ready(cur);
;     PG8_STAGE(PG8_SB(0, 0), cB, voffB); PG8_STAGE(PG8_SB(0, 1), cB + hstep, voffB); PG8_STAGE(PG8_SA(0, 0), cA, voffA); PG8_STAGE(PG8_SA(0, 1), cA + hstep, voffA);
;     if (wr == 1) PG8_BAR;
;     PG8_WAIT_V(2); PG8_BAR;
;     PG8_STAGE(PG8_SB(1, 0), cB + kstep, voffB); PG8_STAGE(PG8_SA(1, 0), cA + kstep, voffA); PG8_STAGE(PG8_SB(1, 1), cB + hstep + kstep, voffB);
;     PG8_WAIT_V(6); PG8_BAR;
.LBB0_135:
	s_add_u32 s8, s8, 0x1ee00000
	s_addc_u32 s9, s9, 0
	s_add_u32 s3, s14, 0x1fe00000
	s_addc_u32 s23, s15, 0
	s_add_u32 s56, s16, 0x21600000
	s_addc_u32 s57, s17, 0
	s_add_u32 s14, s18, 0x2b9d6000
	s_addc_u32 s15, s19, 0
	s_and_b32 s22, s20, 3
	s_add_i32 m0, s52, 0x18000
	v_lshl_add_u64 v[10:11], v[10:11], 0, s[12:13]
	s_lshl_b32 s58, s21, 6
	s_lshl_b32 s18, s21, 13
	s_lshl_b32 s24, s22, 5
	s_lshl_b32 s19, s22, 12
	global_load_lds_dwordx4 v[10:11], off
	v_lshl_add_u64 v[8:9], v[8:9], 0, s[12:13]
	s_add_i32 m0, s52, 0x1a000
	s_add_i32 s59, s52, 0x8000
	s_add_i32 s60, s52, 0xa000
	global_load_lds_dwordx4 v[8:9], off
	v_lshl_add_u64 v[4:5], v[4:5], 0, s[12:13]
	s_mov_b32 m0, s59
	s_add_u32 s16, s40, 0x80080
	global_load_lds_dwordx4 v[4:5], off
	v_lshl_add_u64 v[4:5], v[6:7], 0, s[12:13]
	s_mov_b32 m0, s60
	s_addc_u32 s17, s41, 0
	global_load_lds_dwordx4 v[4:5], off
	s_add_i32 m0, s52, 0x1c000
	v_lshl_add_u64 v[4:5], s[16:17], 0, v[0:1]
	global_load_lds_dwordx4 v[4:5], off
	v_lshl_add_u64 v[4:5], s[16:17], 0, v[208:209]
	s_add_i32 m0, s52, 0x1e000
	v_bfe_u32 v226, v12, 4, 2
	global_load_lds_dwordx4 v[4:5], off
	s_waitcnt vmcnt(8)
	s_barrier
	v_and_b32_e32 v3, 15, v12
	v_lshlrev_b32_e32 v4, 4, v226
	v_lshlrev_b32_e32 v5, 2, v12
	s_cmpk_lt_u32 s10, 0x100
	v_lshl_or_b32 v4, v3, 6, v4
	v_and_b32_e32 v5, 32, v5
	s_cselect_b64 s[16:17], -1, 0
	s_lshl_b32 s10, s20, 4
	s_and_b32 s62, s24, 64
	v_bitop3_b32 v6, v4, s18, v5 bitop3:0xde
	v_bitop3_b32 v227, v4, s19, v5 bitop3:0xde
	s_and_b32 s61, s10, 16
	s_lshl_b32 s10, s62, 1
	s_ashr_i32 s63, s46, 31
	v_lshlrev_b32_e32 v4, 15, v16
	s_add_u32 s18, s3, s10
	v_and_b32_e32 v4, 0xffff0000, v4
	s_addc_u32 s19, s23, 0
	s_lshl_b32 s20, s22, 6
	v_lshl_add_u32 v4, v17, 12, v4
	v_and_b32_e32 v5, 1, v16
	s_add_u32 s0, s0, s20
	v_lshl_or_b32 v4, v5, 6, v4
	s_addc_u32 s1, s1, 0
	v_lshl_add_u32 v210, v18, 1, v4
	v_lshlrev_b32_e32 v4, 15, v13
	s_add_u32 s20, s0, 0x20200000
	v_and_b32_e32 v4, 0xffff0000, v4
	s_waitcnt vmcnt(6)
	s_addc_u32 s21, s1, 0
	s_bitset1_b32 s10, 8
	v_lshl_add_u32 v4, v14, 12, v4
	v_and_b32_e32 v5, 1, v13
	s_add_u32 s22, s3, s10
	v_lshl_or_b32 v4, v5, 6, v4
	s_addc_u32 s23, s23, 0
	v_mov_b32_e32 v211, v2
	v_lshl_add_u32 v212, v15, 1, v4
	v_mov_b32_e32 v213, v2
	s_mov_b32 s64, 0
	v_add_u32_e32 v228, 0, v6
	s_lshl_b32 s65, s24, 1
	s_barrier
	s_branch .LBB0_138

; #define PG8_STAGE(bufoff, gbase, voff) do { _Pragma("unroll") for (int _i = 0; _i < 2; ++_i) \
;         __builtin_amdgcn_global_load_lds((const unsigned*)((const char*)(gbase) + (voff)[_i]), (LAS unsigned*)(lds + (bufoff) + ldsw + _i * 8192), 16, 0, 0); } while (0)
; #define PG8_WAIT_V(n) asm volatile("s_waitcnt vmcnt(" #n ")" ::: "memory")
; #define PG8_BAR __builtin_amdgcn_s_barrier()
; template <class Epi, class Sched, bool FUSED = false, bool APERM = false>
; __device__ __forceinline__ void gemm_phase(int wid_s, LAS unsigned char* lds, const Gemm g, const Sched& S, const Epi& E) {
;     ...
;     const char* cA = (const char*)g.A + (size_t)cur.pm * tstep; const char* cB = (const char*)g.Bt + (size_t)cur.pn * tstep;
;     S.a_ready(cur);
;     PG8_STAGE(PG8_SB(0, 0), cB, voffB); PG8_STAGE(PG8_SB(0, 1), cB + hstep, voffB); PG8_STAGE(PG8_SA(0, 0), cA, voffA); PG8_STAGE(PG8_SA(0, 1), cA + hstep, voffA);
;     if (wr == 1) PG8_BAR;
;     PG8_WAIT_V(2); PG8_BAR;
;     PG8_STAGE(PG8_SB(1, 0), cB + kstep, voffB); PG8_STAGE(PG8_SA(1, 0), cA + kstep, voffA); PG8_STAGE(PG8_SB(1, 1), cB + hstep + kstep, voffB);
;     PG8_WAIT_V(6); PG8_BAR;
.LBB0_332:
	s_add_u32 s6, s6, 0x1ee00000
	s_addc_u32 s7, s7, 0
	s_add_u32 s1, s8, 0x1fe00000
	s_addc_u32 s22, s9, 0
	s_add_u32 s52, s14, 0x21600000
	s_addc_u32 s53, s15, 0
	v_bfe_u32 v226, v15, 4, 2
	s_add_u32 s8, s16, 0x2b9d6000
	v_and_b32_e32 v3, 15, v15
	v_lshlrev_b32_e32 v19, 4, v226
	v_lshlrev_b32_e32 v15, 2, v15
	s_addc_u32 s9, s17, 0
	s_and_b32 s23, s20, 3
	v_lshl_or_b32 v19, v3, 6, v19
	s_lshl_b32 s14, s21, 13
	v_and_b32_e32 v15, 32, v15
	s_add_i32 m0, s48, 0x18000
	v_lshl_add_u64 v[10:11], v[10:11], 0, s[12:13]
	s_lshl_b32 s54, s21, 6
	v_bitop3_b32 v20, v19, s14, v15 bitop3:0xde
	s_lshl_b32 s24, s23, 5
	s_lshl_b32 s14, s23, 12
	global_load_lds_dwordx4 v[10:11], off
	v_lshl_add_u64 v[8:9], v[8:9], 0, s[12:13]
	s_add_i32 m0, s48, 0x1a000
	s_add_i32 s55, s48, 0x8000
	s_add_i32 s56, s48, 0xa000
	v_bitop3_b32 v227, v19, s14, v15 bitop3:0xde
	global_load_lds_dwordx4 v[8:9], off
	v_lshl_add_u64 v[4:5], v[4:5], 0, s[12:13]
	s_mov_b32 m0, s55
	s_add_u32 s14, s36, 0x80080
	global_load_lds_dwordx4 v[4:5], off
	v_lshl_add_u64 v[4:5], v[6:7], 0, s[12:13]
	s_mov_b32 m0, s56
	s_addc_u32 s15, s37, 0
	global_load_lds_dwordx4 v[4:5], off
	s_add_i32 m0, s48, 0x1c000
	v_lshl_add_u64 v[4:5], s[14:15], 0, v[0:1]
	global_load_lds_dwordx4 v[4:5], off
	v_lshl_add_u64 v[4:5], s[14:15], 0, v[208:209]
	s_add_i32 m0, s48, 0x1e000
	s_cmpk_lt_u32 s10, 0x100
	global_load_lds_dwordx4 v[4:5], off
	s_waitcnt vmcnt(8)
	s_barrier
	s_cselect_b64 s[14:15], -1, 0
	s_lshl_b32 s10, s20, 4
	s_and_b32 s58, s24, 64
	s_and_b32 s57, s10, 16
	s_lshl_b32 s10, s58, 1
	s_ashr_i32 s59, s42, 31
	v_lshlrev_b32_e32 v4, 15, v16
	s_add_u32 s16, s1, s10
	v_and_b32_e32 v4, 0xffff0000, v4
	s_addc_u32 s17, s22, 0
	s_lshl_b32 s20, s23, 6
	v_lshl_add_u32 v4, v17, 12, v4
	v_and_b32_e32 v5, 1, v16
	s_add_u32 s18, s18, s20
	v_lshl_or_b32 v4, v5, 6, v4
	s_addc_u32 s19, s19, 0
	v_lshl_add_u32 v210, v18, 1, v4
	v_lshlrev_b32_e32 v4, 15, v12
	s_add_u32 s18, s18, 0x20200000
	v_and_b32_e32 v4, 0xffff0000, v4
	s_waitcnt vmcnt(6)
	s_addc_u32 s19, s19, 0
	s_bitset1_b32 s10, 8
	v_lshl_add_u32 v4, v13, 12, v4
	v_and_b32_e32 v5, 1, v12
	s_add_u32 s20, s1, s10
	v_lshl_or_b32 v4, v5, 6, v4
	s_addc_u32 s21, s22, 0
	v_mov_b32_e32 v211, v2
	v_lshl_add_u32 v212, v14, 1, v4
	v_mov_b32_e32 v213, v2
	s_mov_b32 s10, 0
	v_add_u32_e32 v228, 0, v20
	s_lshl_b32 s60, s24, 1
	s_barrier
	s_branch .LBB0_335

; #define PG8_STAGE(bufoff, gbase, voff) do { _Pragma("unroll") for (int _i = 0; _i < 2; ++_i) \
;         __builtin_amdgcn_global_load_lds((const unsigned*)((const char*)(gbase) + (voff)[_i]), (LAS unsigned*)(lds + (bufoff) + ldsw + _i * 8192), 16, 0, 0); } while (0)
; #define PG8_WAIT_V(n) asm volatile("s_waitcnt vmcnt(" #n ")" ::: "memory")
; #define PG8_BAR __builtin_amdgcn_s_barrier()
; template <class Epi, class Sched, bool FUSED = false, bool APERM = false>
; __device__ __forceinline__ void gemm_phase(int wid_s, LAS unsigned char* lds, const Gemm g, const Sched& S, const Epi& E) {
;     ...
;     const char* cA = (const char*)g.A + (size_t)cur.pm * tstep; const char* cB = (const char*)g.Bt + (size_t)cur.pn * tstep;
;     S.a_ready(cur);
;     PG8_STAGE(PG8_SB(0, 0), cB, voffB); PG8_STAGE(PG8_SB(0, 1), cB + hstep, voffB); PG8_STAGE(PG8_SA(0, 0), cA, voffA); PG8_STAGE(PG8_SA(0, 1), cA + hstep, voffA);
;     if (wr == 1) PG8_BAR;
;     PG8_WAIT_V(2); PG8_BAR;
;     PG8_STAGE(PG8_SB(1, 0), cB + kstep, voffB); PG8_STAGE(PG8_SA(1, 0), cA + kstep, voffA); PG8_STAGE(PG8_SB(1, 1), cB + hstep + kstep, voffB);
;     PG8_WAIT_V(6); PG8_BAR;
.LBB0_572:
	v_bfe_u32 v138, v18, 4, 2
	s_sext_i32_i8 s44, s4
	s_add_u32 s4, s0, 0x22600000
	v_and_b32_e32 v3, 15, v18
	v_lshlrev_b32_e32 v19, 4, v138
	v_lshlrev_b32_e32 v18, 2, v18
	s_addc_u32 s5, s1, 0
	v_lshl_or_b32 v19, v3, 6, v19
	s_lshl_b32 s0, s6, 13
	v_and_b32_e32 v18, 32, v18
	v_bitop3_b32 v20, v19, s0, v18 bitop3:0xde
	s_lshl_b32 s0, s7, 5
	s_and_b32 s9, s0, 0x60
	s_add_i32 m0, s21, 0x18000
	v_lshl_add_u64 v[10:11], v[10:11], 0, s[12:13]
	s_lshl_b32 s40, s6, 6
	s_lshl_b32 s0, s9, 7
	global_load_lds_dwordx4 v[10:11], off
	v_lshl_add_u64 v[8:9], v[8:9], 0, s[12:13]
	s_add_i32 m0, s21, 0x1a000
	s_add_i32 s41, s21, 0x8000
	s_add_i32 s42, s21, 0xa000
	v_bitop3_b32 v139, v19, s0, v18 bitop3:0xde
	global_load_lds_dwordx4 v[8:9], off
	v_lshl_add_u64 v[4:5], v[4:5], 0, s[12:13]
	s_mov_b32 m0, s41
	s_add_u32 s0, s22, 0x20080
	global_load_lds_dwordx4 v[4:5], off
	v_lshl_add_u64 v[4:5], v[6:7], 0, s[12:13]
	s_mov_b32 m0, s42
	s_addc_u32 s1, s23, 0
	global_load_lds_dwordx4 v[4:5], off
	s_add_i32 m0, s21, 0x1c000
	v_lshl_add_u64 v[4:5], s[0:1], 0, v[0:1]
	global_load_lds_dwordx4 v[4:5], off
	v_lshl_add_u64 v[4:5], s[0:1], 0, v[132:133]
	s_add_i32 m0, s21, 0x1e000
	s_cmpk_lt_u32 s8, 0x100
	global_load_lds_dwordx4 v[4:5], off
	s_waitcnt vmcnt(8)
	s_barrier
	v_lshlrev_b32_e32 v4, 13, v15
	v_and_b32_e32 v4, 0xffffc000, v4
	v_lshl_add_u32 v4, v16, 10, v4
	v_and_b32_e32 v5, 1, v15
	v_lshl_or_b32 v4, v5, 6, v4
	v_lshl_add_u32 v134, v17, 1, v4
	v_lshlrev_b32_e32 v4, 13, v12
	v_and_b32_e32 v4, 0xffffc000, v4
	s_waitcnt vmcnt(6)
	v_lshl_add_u32 v4, v13, 10, v4
	v_and_b32_e32 v5, 1, v12
	v_lshl_or_b32 v4, v5, 6, v4
	s_cselect_b64 s[6:7], -1, 0
	v_mov_b32_e32 v135, v2
	v_lshl_add_u32 v136, v14, 1, v4
	v_mov_b32_e32 v137, v2
	s_mov_b32 s43, 0
	v_add_u32_e32 v140, 0, v20
	s_lshl_b32 s10, s9, 1
	s_barrier
	s_branch .LBB0_575

; #define PG8_STAGE(bufoff, gbase, voff) do { _Pragma("unroll") for (int _i = 0; _i < 2; ++_i) \
;         __builtin_amdgcn_global_load_lds((const unsigned*)((const char*)(gbase) + (voff)[_i]), (LAS unsigned*)(lds + (bufoff) + ldsw + _i * 8192), 16, 0, 0); } while (0)
; #define PG8_WAIT_V(n) asm volatile("s_waitcnt vmcnt(" #n ")" ::: "memory")
; #define PG8_BAR __builtin_amdgcn_s_barrier()
; template <class Epi, class Sched, bool FUSED = false, bool APERM = false>
; __device__ __forceinline__ void gemm_phase(int wid_s, LAS unsigned char* lds, const Gemm g, const Sched& S, const Epi& E) {
;     ...
;     f32x4 acc[2][2][4][2];
; #pragma unroll
;     for (int a = 0; a < 2; ++a)
; #pragma unroll
;         for (int b = 0; b < 2; ++b)
; #pragma unroll
;             for (int m = 0; m < 4; ++m)
; #pragma unroll
;                 for (int n = 0; n < 2; ++n) acc[a][b][m][n] = (f32x4){0.f, 0.f, 0.f, 0.f};
;     bf16x8 At[4][2], B0[2][2], B1[2][2];
;     const char* cA = (const char*)g.A + (size_t)cur.pm * tstep; const char* cB = (const char*)g.Bt + (size_t)cur.pn * tstep;
;     S.a_ready(cur);
;     PG8_STAGE(PG8_SB(0, 0), cB, voffB); PG8_STAGE(PG8_SB(0, 1), cB + hstep, voffB); PG8_STAGE(PG8_SA(0, 0), cA, voffA); PG8_STAGE(PG8_SA(0, 1), cA + hstep, voffA);
;     if (wr == 1) PG8_BAR;
;     PG8_WAIT_V(2); PG8_BAR;
;     PG8_STAGE(PG8_SB(1, 0), cB + kstep, voffB); PG8_STAGE(PG8_SA(1, 0), cA + kstep, voffA); PG8_STAGE(PG8_SB(1, 1), cB + hstep + kstep, voffB);
;     PG8_WAIT_V(6); PG8_BAR;
.LBB0_645:
	v_bfe_u32 v220, v3, 4, 2
	v_and_b32_e32 v221, 15, v3
	v_lshlrev_b32_e32 v20, 4, v220
	v_lshlrev_b32_e32 v3, 2, v3
	s_sext_i32_i8 s16, s0
	s_and_b32 s10, s17, 3
	v_lshl_or_b32 v20, v221, 6, v20
	s_lshl_b32 s0, s1, 13
	v_and_b32_e32 v3, 32, v3
	s_add_i32 m0, s15, 0x18000
	v_lshl_add_u64 v[10:11], v[10:11], 0, s[12:13]
	s_lshl_b32 s53, s1, 6
	v_bitop3_b32 v21, v20, s0, v3 bitop3:0xde
	s_lshl_b32 s0, s10, 12
	global_load_lds_dwordx4 v[10:11], off
	v_lshl_add_u64 v[8:9], v[8:9], 0, s[12:13]
	s_add_i32 m0, s15, 0x1a000
	s_add_i32 s54, s15, 0x8000
	s_add_i32 s55, s15, 0xa000
	v_bitop3_b32 v3, v20, s0, v3 bitop3:0xde
	global_load_lds_dwordx4 v[8:9], off
	v_lshl_add_u64 v[4:5], v[4:5], 0, s[12:13]
	s_mov_b32 m0, s54
	s_add_u32 s0, s36, 0x80080
	global_load_lds_dwordx4 v[4:5], off
	v_lshl_add_u64 v[4:5], v[6:7], 0, s[12:13]
	s_mov_b32 m0, s55
	s_addc_u32 s1, s37, 0
	global_load_lds_dwordx4 v[4:5], off
	s_add_i32 m0, s15, 0x1c000
	v_lshl_add_u64 v[4:5], s[0:1], 0, v[0:1]
	global_load_lds_dwordx4 v[4:5], off
	v_lshl_add_u64 v[4:5], s[0:1], 0, v[132:133]
	s_add_i32 m0, s15, 0x1e000
	s_cmpk_lt_u32 s42, 0x100
	global_load_lds_dwordx4 v[4:5], off
	s_waitcnt vmcnt(8)
	s_barrier
	v_lshlrev_b32_e32 v4, 14, v16
	v_and_b32_e32 v4, 0x7fff8000, v4
	v_lshl_add_u32 v4, v17, 11, v4
	v_or_b32_e32 v4, v4, v18
	v_add_lshl_u32 v134, v4, v19, 1
	v_lshlrev_b32_e32 v4, 14, v12
	v_and_b32_e32 v4, 0x7fff8000, v4
	v_lshl_add_u32 v4, v13, 11, v4
	s_waitcnt vmcnt(6)
	v_or_b32_e32 v4, v4, v14
	v_add_lshl_u32 v136, v4, v15, 1
	v_mov_b32_e32 v4, 0
	s_cselect_b64 s[22:23], -1, 0
	v_mov_b32_e32 v135, v2
	v_mov_b32_e32 v137, v2
	s_mov_b32 s57, 0
	v_add_u32_e32 v142, 0, v21
	v_mov_b32_e32 v5, v4
	v_mov_b64_e32 v[6:7], 0
	v_mov_b64_e32 v[8:9], 0
	v_mov_b64_e32 v[10:11], 0
	v_mov_b64_e32 v[20:21], 0
	v_mov_b64_e32 v[22:23], 0
	v_mov_b64_e32 v[24:25], 0
	v_mov_b64_e32 v[26:27], 0
	v_mov_b64_e32 v[36:37], 0
	v_mov_b64_e32 v[38:39], 0
	v_mov_b64_e32 v[40:41], 0
	v_mov_b64_e32 v[42:43], 0
	v_mov_b64_e32 v[52:53], 0
	v_mov_b64_e32 v[54:55], 0
	v_mov_b64_e32 v[56:57], 0
	v_mov_b64_e32 v[58:59], 0
	v_mov_b64_e32 v[12:13], 0
	v_mov_b64_e32 v[14:15], 0
	v_mov_b64_e32 v[16:17], 0
	v_mov_b64_e32 v[18:19], 0
	v_mov_b64_e32 v[28:29], 0
	v_mov_b64_e32 v[30:31], 0
	v_mov_b64_e32 v[32:33], 0
	v_mov_b64_e32 v[34:35], 0
	v_mov_b64_e32 v[44:45], 0
	v_mov_b64_e32 v[46:47], 0
	v_mov_b64_e32 v[48:49], 0
	v_mov_b64_e32 v[50:51], 0
	v_mov_b64_e32 v[60:61], 0
	v_mov_b64_e32 v[62:63], 0
	v_mov_b64_e32 v[64:65], 0
	v_mov_b64_e32 v[66:67], 0
	v_mov_b64_e32 v[68:69], 0
	v_mov_b64_e32 v[70:71], 0
	v_mov_b64_e32 v[72:73], 0
	v_mov_b64_e32 v[74:75], 0
	v_mov_b64_e32 v[84:85], 0
	v_mov_b64_e32 v[86:87], 0
	v_mov_b64_e32 v[88:89], 0
	v_mov_b64_e32 v[90:91], 0
	v_mov_b64_e32 v[100:101], 0
	v_mov_b64_e32 v[102:103], 0
	v_mov_b64_e32 v[104:105], 0
	v_mov_b64_e32 v[106:107], 0
	v_mov_b64_e32 v[116:117], 0
	v_mov_b64_e32 v[118:119], 0
	v_mov_b64_e32 v[120:121], 0
	v_mov_b64_e32 v[122:123], 0
	v_mov_b64_e32 v[76:77], 0
	v_mov_b64_e32 v[78:79], 0
	v_mov_b64_e32 v[80:81], 0
	v_mov_b64_e32 v[82:83], 0
	v_mov_b64_e32 v[92:93], 0
	v_mov_b64_e32 v[94:95], 0
	v_mov_b64_e32 v[96:97], 0
	v_mov_b64_e32 v[98:99], 0
	v_mov_b64_e32 v[108:109], 0
	v_mov_b64_e32 v[110:111], 0
	v_mov_b64_e32 v[112:113], 0
	v_mov_b64_e32 v[114:115], 0
	v_mov_b64_e32 v[124:125], 0
	v_mov_b64_e32 v[126:127], 0
	v_mov_b64_e32 v[128:129], 0
	v_mov_b64_e32 v[130:131], 0
	s_barrier

; #define PG8_STAGE(bufoff, gbase, voff) do { _Pragma("unroll") for (int _i = 0; _i < 2; ++_i) \
;         __builtin_amdgcn_global_load_lds((const unsigned*)((const char*)(gbase) + (voff)[_i]), (LAS unsigned*)(lds + (bufoff) + ldsw + _i * 8192), 16, 0, 0); } while (0)
; #define PG8_WAIT_V(n) asm volatile("s_waitcnt vmcnt(" #n ")" ::: "memory")
; #define PG8_BAR __builtin_amdgcn_s_barrier()
; template <class Epi, class Sched, bool FUSED = false, bool APERM = false>
; __device__ __forceinline__ void gemm_phase(int wid_s, LAS unsigned char* lds, const Gemm g, const Sched& S, const Epi& E) {
;     ...
;     const char* cA = (const char*)g.A + (size_t)cur.pm * tstep; const char* cB = (const char*)g.Bt + (size_t)cur.pn * tstep;
;     S.a_ready(cur);
;     PG8_STAGE(PG8_SB(0, 0), cB, voffB); PG8_STAGE(PG8_SB(0, 1), cB + hstep, voffB); PG8_STAGE(PG8_SA(0, 0), cA, voffA); PG8_STAGE(PG8_SA(0, 1), cA + hstep, voffA);
;     if (wr == 1) PG8_BAR;
;     PG8_WAIT_V(2); PG8_BAR;
;     PG8_STAGE(PG8_SB(1, 0), cB + kstep, voffB); PG8_STAGE(PG8_SA(1, 0), cA + kstep, voffA); PG8_STAGE(PG8_SB(1, 1), cB + hstep + kstep, voffB);
;     PG8_WAIT_V(6); PG8_BAR;
.LBB0_748:
	v_readlane_b32 s56, v253, 21
	s_mul_i32 s5, s86, 0x20400
	v_readlane_b32 s60, v253, 25
	s_mul_hi_u32 s3, s86, 0x20400
	v_readlane_b32 s61, v253, 26
	s_add_u32 s14, s60, s5
	v_readlane_b32 s62, v253, 27
	s_addc_u32 s15, s61, s3
	s_mul_i32 s5, s86, 0xac00
	v_readlane_b32 s63, v253, 28
	s_mul_hi_u32 s3, s86, 0xac00
	s_add_u32 s16, s62, s5
	s_addc_u32 s17, s63, s3
	s_add_u32 s18, s14, 0xac00
	s_addc_u32 s19, s15, 0
	s_add_u32 s20, s14, 0x15800
	s_addc_u32 s21, s15, 0
	s_add_u32 s22, s22, 0x24e00000
	s_addc_u32 s23, s23, 0
	v_and_b32_e32 v3, 15, v17
	v_readlane_b32 s57, v253, 22
	s_add_u32 s56, s0, 0x2a400000
	v_bfe_u32 v243, v17, 4, 2
	v_lshlrev_b32_e32 v23, 6, v3
	v_lshlrev_b32_e32 v17, 2, v17
	s_addc_u32 s57, s1, 0
	v_lshl_or_b32 v23, v243, 4, v23
	s_lshl_b32 s0, s50, 13
	v_and_b32_e32 v17, 32, v17
	v_readlane_b32 s58, v253, 23
	v_bitop3_b32 v24, v23, s0, v17 bitop3:0xde
	s_lshl_b32 s0, s25, 5
	v_readlane_b32 s59, v253, 24
	s_and_b32 s58, s0, 0x60
	s_add_i32 m0, s52, 0x18000
	v_lshl_add_u64 v[10:11], v[10:11], 0, s[12:13]
	s_lshl_b32 s0, s58, 7
	global_load_lds_dwordx4 v[10:11], off
	v_lshl_add_u64 v[8:9], v[8:9], 0, s[12:13]
	s_add_i32 m0, s52, 0x1a000
	s_add_i32 s59, s52, 0x8000
	s_add_i32 s60, s52, 0xa000
	v_bitop3_b32 v244, v23, s0, v17 bitop3:0xde
	global_load_lds_dwordx4 v[8:9], off
	v_lshl_add_u64 v[4:5], v[4:5], 0, s[12:13]
	s_mov_b32 m0, s59
	s_add_u32 s0, s36, 0x80080
	global_load_lds_dwordx4 v[4:5], off
	v_lshl_add_u64 v[4:5], v[6:7], 0, s[12:13]
	s_mov_b32 m0, s60
	s_addc_u32 s1, s37, 0
	global_load_lds_dwordx4 v[4:5], off
	s_add_i32 m0, s52, 0x1c000
	v_lshl_add_u64 v[4:5], s[0:1], 0, v[208:209]
	global_load_lds_dwordx4 v[4:5], off
	v_lshl_add_u64 v[4:5], s[0:1], 0, v[212:213]
	s_add_i32 m0, s52, 0x1e000
	s_mov_b64 s[0:1], 0x80080
	global_load_lds_dwordx4 v[4:5], off
	s_waitcnt vmcnt(8)
	s_barrier
	v_and_b32_e32 v5, 1, v18
	v_add3_u32 v4, v20, v21, v22
	v_lshlrev_b32_e32 v5, 6, v5
	v_lshl_or_b32 v4, v4, 12, v5
	v_lshl_add_u32 v4, v19, 1, v4
	v_mov_b32_e32 v5, v2
	v_lshl_add_u64 v[214:215], v[4:5], 0, s[0:1]
	v_and_b32_e32 v5, 1, v12
	v_add3_u32 v4, v14, v15, v16
	v_lshlrev_b32_e32 v5, 6, v5
	s_waitcnt vmcnt(6)
	v_lshl_or_b32 v4, v4, 12, v5
	s_cmpk_lt_u32 s24, 0x100
	v_lshl_add_u32 v4, v13, 1, v4
	v_mov_b32_e32 v5, v2
	s_cselect_b64 s[24:25], -1, 0
	s_ashr_i32 s61, s10, 31
	v_lshl_add_u64 v[216:217], v[4:5], 0, s[0:1]
	s_mov_b32 s62, 0
	v_add_u32_e32 v245, 0, v24
	v_readlane_b32 s64, v253, 29
	v_readlane_b32 s65, v253, 30
	v_readlane_b32 s66, v253, 31
	v_readlane_b32 s67, v253, 32
	v_readlane_b32 s68, v253, 33
	v_readlane_b32 s69, v253, 34
	v_readlane_b32 s70, v253, 35
	v_readlane_b32 s71, v253, 36
	s_barrier
	s_branch .LBB0_751

; #define PG8_STAGE(bufoff, gbase, voff) do { _Pragma("unroll") for (int _i = 0; _i < 2; ++_i) \
;         __builtin_amdgcn_global_load_lds((const unsigned*)((const char*)(gbase) + (voff)[_i]), (LAS unsigned*)(lds + (bufoff) + ldsw + _i * 8192), 16, 0, 0); } while (0)
; #define PG8_WAIT_V(n) asm volatile("s_waitcnt vmcnt(" #n ")" ::: "memory")
; #define PG8_BAR __builtin_amdgcn_s_barrier()
; template <class Epi, class Sched, bool FUSED = false, bool APERM = false>
; __device__ __forceinline__ void gemm_phase(int wid_s, LAS unsigned char* lds, const Gemm g, const Sched& S, const Epi& E) {
;     ...
;     f32x4 acc[2][2][4][2];
; #pragma unroll
;     for (int a = 0; a < 2; ++a)
; #pragma unroll
;         for (int b = 0; b < 2; ++b)
; #pragma unroll
;             for (int m = 0; m < 4; ++m)
; #pragma unroll
;                 for (int n = 0; n < 2; ++n) acc[a][b][m][n] = (f32x4){0.f, 0.f, 0.f, 0.f};
;     bf16x8 At[4][2], B0[2][2], B1[2][2];
;     const char* cA = (const char*)g.A + (size_t)cur.pm * tstep; const char* cB = (const char*)g.Bt + (size_t)cur.pn * tstep;
;     S.a_ready(cur);
;     PG8_STAGE(PG8_SB(0, 0), cB, voffB); PG8_STAGE(PG8_SB(0, 1), cB + hstep, voffB); PG8_STAGE(PG8_SA(0, 0), cA, voffA); PG8_STAGE(PG8_SA(0, 1), cA + hstep, voffA);
;     if (wr == 1) PG8_BAR;
;     PG8_WAIT_V(2); PG8_BAR;
;     PG8_STAGE(PG8_SB(1, 0), cB + kstep, voffB); PG8_STAGE(PG8_SA(1, 0), cA + kstep, voffA); PG8_STAGE(PG8_SB(1, 1), cB + hstep + kstep, voffB);
;     PG8_WAIT_V(6); PG8_BAR;
.LBB0_917:
	v_bfe_u32 v220, v3, 4, 2
	v_and_b32_e32 v221, 15, v3
	v_lshlrev_b32_e32 v20, 4, v220
	v_lshlrev_b32_e32 v3, 2, v3
	s_and_b32 s10, s21, 3
	s_lshl_b32 s53, s0, 6
	v_lshl_or_b32 v20, v221, 6, v20
	s_lshl_b32 s0, s0, 13
	v_and_b32_e32 v3, 32, v3
	s_add_i32 m0, s49, 0x18000
	v_lshl_add_u64 v[10:11], v[10:11], 0, s[12:13]
	v_bitop3_b32 v21, v20, s0, v3 bitop3:0xde
	s_lshl_b32 s0, s10, 12
	global_load_lds_dwordx4 v[10:11], off
	v_lshl_add_u64 v[8:9], v[8:9], 0, s[12:13]
	s_add_i32 m0, s49, 0x1a000
	s_add_i32 s54, s49, 0x8000
	s_add_i32 s55, s49, 0xa000
	v_bitop3_b32 v3, v20, s0, v3 bitop3:0xde
	global_load_lds_dwordx4 v[8:9], off
	v_lshl_add_u64 v[4:5], v[4:5], 0, s[12:13]
	s_mov_b32 m0, s54
	s_add_u32 s0, s34, 0x158080
	s_sext_i32_i8 s20, s1
	global_load_lds_dwordx4 v[4:5], off
	v_lshl_add_u64 v[4:5], v[6:7], 0, s[12:13]
	s_mov_b32 m0, s55
	s_addc_u32 s1, s35, 0
	global_load_lds_dwordx4 v[4:5], off
	s_add_i32 m0, s49, 0x1c000
	v_lshl_add_u64 v[4:5], s[0:1], 0, v[0:1]
	global_load_lds_dwordx4 v[4:5], off
	v_lshl_add_u64 v[4:5], s[0:1], 0, v[132:133]
	s_add_i32 m0, s49, 0x1e000
	s_movk_i32 s2, 0x1580
	global_load_lds_dwordx4 v[4:5], off
	s_waitcnt vmcnt(8)
	s_barrier
	v_lshrrev_b32_e32 v5, 1, v16
	v_mul_lo_u32 v4, v18, s2
	s_mov_b32 s3, 0x15800
	v_mad_u64_u32 v[4:5], s[0:1], v5, s3, v[4:5]
	v_or_b32_e32 v4, v4, v17
	v_add_lshl_u32 v134, v4, v19, 1
	v_lshrrev_b32_e32 v5, 1, v12
	v_mul_lo_u32 v4, v14, s2
	v_mad_u64_u32 v[4:5], s[0:1], v5, s3, v[4:5]
	s_waitcnt vmcnt(6)
	v_or_b32_e32 v4, v4, v13
	s_cmpk_lt_u32 s40, 0x100
	v_add_lshl_u32 v136, v4, v15, 1
	v_mov_b32_e32 v4, 0
	s_cselect_b64 s[26:27], -1, 0
	v_mov_b32_e32 v135, v2
	v_mov_b32_e32 v137, v2
	s_mov_b32 s59, 0
	v_add_u32_e32 v142, 0, v21
	v_mov_b32_e32 v5, v4
	v_mov_b64_e32 v[6:7], 0
	v_mov_b64_e32 v[8:9], 0
	v_mov_b64_e32 v[10:11], 0
	v_mov_b64_e32 v[20:21], 0
	v_mov_b64_e32 v[22:23], 0
	v_mov_b64_e32 v[24:25], 0
	v_mov_b64_e32 v[26:27], 0
	v_mov_b64_e32 v[36:37], 0
	v_mov_b64_e32 v[38:39], 0
	v_mov_b64_e32 v[40:41], 0
	v_mov_b64_e32 v[42:43], 0
	v_mov_b64_e32 v[52:53], 0
	v_mov_b64_e32 v[54:55], 0
	v_mov_b64_e32 v[56:57], 0
	v_mov_b64_e32 v[58:59], 0
	v_mov_b64_e32 v[12:13], 0
	v_mov_b64_e32 v[14:15], 0
	v_mov_b64_e32 v[16:17], 0
	v_mov_b64_e32 v[18:19], 0
	v_mov_b64_e32 v[28:29], 0
	v_mov_b64_e32 v[30:31], 0
	v_mov_b64_e32 v[32:33], 0
	v_mov_b64_e32 v[34:35], 0
	v_mov_b64_e32 v[44:45], 0
	v_mov_b64_e32 v[46:47], 0
	v_mov_b64_e32 v[48:49], 0
	v_mov_b64_e32 v[50:51], 0
	v_mov_b64_e32 v[60:61], 0
	v_mov_b64_e32 v[62:63], 0
	v_mov_b64_e32 v[64:65], 0
	v_mov_b64_e32 v[66:67], 0
	v_mov_b64_e32 v[68:69], 0
	v_mov_b64_e32 v[70:71], 0
	v_mov_b64_e32 v[72:73], 0
	v_mov_b64_e32 v[74:75], 0
	v_mov_b64_e32 v[84:85], 0
	v_mov_b64_e32 v[86:87], 0
	v_mov_b64_e32 v[88:89], 0
	v_mov_b64_e32 v[90:91], 0
	v_mov_b64_e32 v[100:101], 0
	v_mov_b64_e32 v[102:103], 0
	v_mov_b64_e32 v[104:105], 0
	v_mov_b64_e32 v[106:107], 0
	v_mov_b64_e32 v[116:117], 0
	v_mov_b64_e32 v[118:119], 0
	v_mov_b64_e32 v[120:121], 0
	v_mov_b64_e32 v[122:123], 0
	v_mov_b64_e32 v[76:77], 0
	v_mov_b64_e32 v[78:79], 0
	v_mov_b64_e32 v[80:81], 0
	v_mov_b64_e32 v[82:83], 0
	v_mov_b64_e32 v[92:93], 0
	v_mov_b64_e32 v[94:95], 0
	v_mov_b64_e32 v[96:97], 0
	v_mov_b64_e32 v[98:99], 0
	v_mov_b64_e32 v[108:109], 0
	v_mov_b64_e32 v[110:111], 0
	v_mov_b64_e32 v[112:113], 0
	v_mov_b64_e32 v[114:115], 0
	v_mov_b64_e32 v[124:125], 0
	v_mov_b64_e32 v[126:127], 0
	v_mov_b64_e32 v[128:129], 0
	v_mov_b64_e32 v[130:131], 0
	s_barrier
